# v059 with the attention loop's per-tile barrier moved between the QK and PV MFMA groups: tile write under the QK group, next step's K fragments read under the PV group (no LDS-read latency after the b
# speedup vs baseline: 1.0064x; 1.0064x over previous
.LBB0_496:
	v_ashrrev_i32_e32 v191, 31, v190
	v_lshlrev_b32_e32 v207, 2, v168
	s_waitcnt lgkmcnt(7)
	v_mfma_f32_32x32x16_bf16 v[66:81], v[162:165], v[130:133], v[34:49]
	v_exp_f32_e32 v65, v98
	v_exp_f32_e32 v162, v99
	s_nop 0
	v_cvt_pk_bf16_f32 v98, v65, v162
	v_add_f32_e32 v65, 0, v65
	v_add_f32_e32 v65, v162, v65
	s_waitcnt lgkmcnt(5)
	v_mfma_f32_32x32x16_bf16 v[34:49], v[158:161], v[130:133], v[34:49]
	v_exp_f32_e32 v158, v100
	v_exp_f32_e32 v159, v101
	v_add_f32_e32 v65, v158, v65
	v_cvt_pk_bf16_f32 v99, v158, v159
	v_add_f32_e32 v65, v159, v65
	v_mfma_f32_32x32x16_bf16 v[66:81], v[154:157], v[134:137], v[66:81]
	v_exp_f32_e32 v154, v102
	v_exp_f32_e32 v155, v103
	v_add_f32_e32 v65, v154, v65
	v_cvt_pk_bf16_f32 v100, v154, v155
	v_add_f32_e32 v65, v155, v65
	s_waitcnt lgkmcnt(3)
	v_mfma_f32_32x32x16_bf16 v[66:81], v[126:129], v[138:141], v[66:81]
	v_exp_f32_e32 v104, v104
	v_exp_f32_e32 v105, v105
	v_add_f32_e32 v65, v104, v65
	v_cvt_pk_bf16_f32 v101, v104, v105
	v_add_f32_e32 v65, v105, v65
	s_waitcnt lgkmcnt(2)
	v_mfma_f32_32x32x16_bf16 v[66:81], v[122:125], v[142:145], v[66:81]
	v_exp_f32_e32 v106, v106
	v_exp_f32_e32 v107, v107
	s_nop 0
	v_cvt_pk_bf16_f32 v102, v106, v107
	v_exp_f32_e32 v108, v108
	v_mfma_f32_32x32x16_bf16 v[34:49], v[60:63], v[134:137], v[34:49]
	v_exp_f32_e32 v109, v109
	v_add_f32_e32 v60, v106, v65
	v_add_f32_e32 v60, v107, v60
	v_add_f32_e32 v60, v108, v60
	v_cvt_pk_bf16_f32 v103, v108, v109
	v_exp_f32_e32 v110, v110
	v_exp_f32_e32 v111, v111
	s_waitcnt lgkmcnt(1)
	v_mfma_f32_32x32x16_bf16 v[34:49], v[56:59], v[138:141], v[34:49]
	v_add_f32_e32 v60, v109, v60
	v_add_f32_e32 v60, v110, v60
	v_cvt_pk_bf16_f32 v104, v110, v111
	v_exp_f32_e32 v112, v112
	v_exp_f32_e32 v162, v113
	v_add_f32_e32 v60, v111, v60
	v_add_f32_e32 v65, v112, v60
	v_cvt_pk_bf16_f32 v105, v112, v162
	s_setprio 0
	ds_read_b128 v[56:59], v64 offset:27648
	ds_read_b128 v[60:63], v64 offset:27680
	ds_read_b128 v[106:109], v64 offset:27712
	ds_read_b128 v[110:113], v64 offset:27744
	ds_read_b128 v[122:125], v64 offset:32256
	ds_read_b128 v[126:129], v64 offset:32288
	ds_read_b128 v[154:157], v64 offset:32320
	ds_read_b128 v[158:161], v64 offset:32352
	v_add_f32_e32 v64, v162, v65
	v_exp_f32_e32 v65, v82
	v_exp_f32_e32 v82, v83
	v_exp_f32_e32 v83, v84
	v_exp_f32_e32 v84, v85
	v_add_f32_e32 v64, v65, v64
	v_exp_f32_e32 v85, v86
	v_add_f32_e32 v64, v82, v64
	v_exp_f32_e32 v86, v87
	v_add_f32_e32 v64, v83, v64
	v_exp_f32_e32 v87, v88
	v_add_f32_e32 v64, v84, v64
	v_exp_f32_e32 v88, v89
	v_add_f32_e32 v64, v85, v64
	v_exp_f32_e32 v89, v90
	v_add_f32_e32 v64, v86, v64
	v_exp_f32_e32 v90, v91
	v_add_f32_e32 v64, v87, v64
	v_exp_f32_e32 v91, v92
	v_add_f32_e32 v64, v88, v64
	v_exp_f32_e32 v92, v93
	v_add_f32_e32 v64, v89, v64
	v_exp_f32_e32 v93, v94
	v_add_f32_e32 v64, v90, v64
	v_exp_f32_e32 v94, v95
	v_add_f32_e32 v64, v91, v64
	v_exp_f32_e32 v95, v96
	v_add_f32_e32 v64, v92, v64
	v_exp_f32_e32 v96, v97
	v_add_f32_e32 v64, v93, v64
	v_add_f32_e32 v64, v94, v64
	v_add_f32_e32 v64, v95, v64
	v_add_f32_e32 v64, v96, v64
	v_cvt_pk_bf16_f32 v82, v65, v82
	v_cvt_pk_bf16_f32 v83, v83, v84
	v_cvt_pk_bf16_f32 v84, v85, v86
	v_cvt_pk_bf16_f32 v85, v87, v88
	v_cvt_pk_bf16_f32 v86, v89, v90
	v_cvt_pk_bf16_f32 v87, v91, v92
	v_cvt_pk_bf16_f32 v88, v93, v94
	v_cvt_pk_bf16_f32 v89, v95, v96
	s_setprio 1
	s_waitcnt lgkmcnt(7)
	v_mfma_f32_32x32x16_bf16 v[18:33], v[56:59], v[98:101], v[18:33]
	v_add_f32_e32 v210, v50, v64
	s_waitcnt lgkmcnt(3)
	v_mfma_f32_32x32x16_bf16 v[2:17], v[122:125], v[98:101], v[2:17]
	v_mfma_f32_32x32x16_bf16 v[18:33], v[60:63], v[102:105], v[18:33]
	s_waitcnt lgkmcnt(2)
	v_mfma_f32_32x32x16_bf16 v[2:17], v[126:129], v[102:105], v[2:17]
	v_mfma_f32_32x32x16_bf16 v[18:33], v[106:109], v[82:85], v[18:33]
	s_waitcnt lgkmcnt(1)
	v_mfma_f32_32x32x16_bf16 v[2:17], v[154:157], v[82:85], v[2:17]
	v_mfma_f32_32x32x16_bf16 v[18:33], v[110:113], v[86:89], v[18:33]
	s_waitcnt lgkmcnt(0)
	v_mfma_f32_32x32x16_bf16 v[2:17], v[158:161], v[86:89], v[2:17]
	v_mfma_f32_32x32x16_bf16 v[34:49], v[52:55], v[142:145], v[34:49]
	s_setprio 0
	s_movk_i32 s2, 0x4800
	s_mov_b32 s3, 0
	s_mov_b32 s0, 0x9000
	s_mov_b32 s10, 6
	v_mov_b32_e32 v50, v51
	v_mov_b32_e32 v52, v51
	v_mov_b32_e32 v53, v51
	v_mov_b32_e32 v54, v51
	v_mov_b32_e32 v55, v51
	v_mov_b32_e32 v56, v51
	v_mov_b32_e32 v57, v51
	v_mov_b32_e32 v58, v51
	v_mov_b32_e32 v59, v51
	v_mov_b32_e32 v60, v51
	v_mov_b32_e32 v61, v51
	v_mov_b32_e32 v62, v51
	v_mov_b32_e32 v63, v51
	v_mov_b32_e32 v64, v51
	v_mov_b32_e32 v65, v51
	s_waitcnt vmcnt(3)
	ds_write_b128 v169, v[114:117]
	s_waitcnt vmcnt(2)
	ds_write_b128 v170, v[118:121] offset:9216
	v_readlane_b32 s1, v255, 20
	s_nop 3
	s_cmp_lt_u32 s1, 0x42400000
	s_cbranch_scc0 .Lattn_online_pre
	v_sub_f32_e32 v50, s1, v206
	v_exp_f32_e64 v52, -v50
	v_mov_b32_e32 v206, s1
	v_readfirstlane_b32 s3, v194
	v_readfirstlane_b32 s12, v195
	v_readfirstlane_b32 s15, v208
	v_readfirstlane_b32 s23, v209
	v_add_u32_e32 v248, 0x2400, v0
	v_pk_add_f32 v[66:67], v[66:67], v[50:51] op_sel_hi:[1,0] neg_lo:[0,1] neg_hi:[0,1]
	v_pk_add_f32 v[68:69], v[68:69], v[50:51] op_sel_hi:[1,0] neg_lo:[0,1] neg_hi:[0,1]
	v_pk_add_f32 v[70:71], v[70:71], v[50:51] op_sel_hi:[1,0] neg_lo:[0,1] neg_hi:[0,1]
	v_pk_add_f32 v[72:73], v[72:73], v[50:51] op_sel_hi:[1,0] neg_lo:[0,1] neg_hi:[0,1]
	v_pk_add_f32 v[74:75], v[74:75], v[50:51] op_sel_hi:[1,0] neg_lo:[0,1] neg_hi:[0,1]
	v_pk_add_f32 v[76:77], v[76:77], v[50:51] op_sel_hi:[1,0] neg_lo:[0,1] neg_hi:[0,1]
	v_pk_add_f32 v[78:79], v[78:79], v[50:51] op_sel_hi:[1,0] neg_lo:[0,1] neg_hi:[0,1]
	v_pk_add_f32 v[80:81], v[80:81], v[50:51] op_sel_hi:[1,0] neg_lo:[0,1] neg_hi:[0,1]
	v_pk_add_f32 v[34:35], v[34:35], v[50:51] op_sel_hi:[1,0] neg_lo:[0,1] neg_hi:[0,1]
	v_pk_add_f32 v[36:37], v[36:37], v[50:51] op_sel_hi:[1,0] neg_lo:[0,1] neg_hi:[0,1]
	v_pk_add_f32 v[38:39], v[38:39], v[50:51] op_sel_hi:[1,0] neg_lo:[0,1] neg_hi:[0,1]
	v_pk_add_f32 v[40:41], v[40:41], v[50:51] op_sel_hi:[1,0] neg_lo:[0,1] neg_hi:[0,1]
	v_pk_add_f32 v[42:43], v[42:43], v[50:51] op_sel_hi:[1,0] neg_lo:[0,1] neg_hi:[0,1]
	v_pk_add_f32 v[44:45], v[44:45], v[50:51] op_sel_hi:[1,0] neg_lo:[0,1] neg_hi:[0,1]
	v_pk_add_f32 v[46:47], v[46:47], v[50:51] op_sel_hi:[1,0] neg_lo:[0,1] neg_hi:[0,1]
	v_pk_add_f32 v[48:49], v[48:49], v[50:51] op_sel_hi:[1,0] neg_lo:[0,1] neg_hi:[0,1]
	v_subrev_u32_e32 v252, s3, v194
	v_subrev_u32_e32 v253, s15, v208
	v_pk_mul_f32 v[2:3], v[2:3], v[52:53] op_sel_hi:[1,0]
	v_pk_mul_f32 v[4:5], v[4:5], v[52:53] op_sel_hi:[1,0]
	v_pk_mul_f32 v[6:7], v[6:7], v[52:53] op_sel_hi:[1,0]
	v_pk_mul_f32 v[8:9], v[8:9], v[52:53] op_sel_hi:[1,0]
	v_pk_mul_f32 v[10:11], v[10:11], v[52:53] op_sel_hi:[1,0]
	v_pk_mul_f32 v[12:13], v[12:13], v[52:53] op_sel_hi:[1,0]
	v_pk_mul_f32 v[14:15], v[14:15], v[52:53] op_sel_hi:[1,0]
	v_pk_mul_f32 v[16:17], v[16:17], v[52:53] op_sel_hi:[1,0]
	v_pk_mul_f32 v[18:19], v[18:19], v[52:53] op_sel_hi:[1,0]
	v_pk_mul_f32 v[20:21], v[20:21], v[52:53] op_sel_hi:[1,0]
	v_pk_mul_f32 v[22:23], v[22:23], v[52:53] op_sel_hi:[1,0]
	v_pk_mul_f32 v[24:25], v[24:25], v[52:53] op_sel_hi:[1,0]
	v_pk_mul_f32 v[26:27], v[26:27], v[52:53] op_sel_hi:[1,0]
	v_pk_mul_f32 v[28:29], v[28:29], v[52:53] op_sel_hi:[1,0]
	v_pk_mul_f32 v[30:31], v[30:31], v[52:53] op_sel_hi:[1,0]
	v_pk_mul_f32 v[32:33], v[32:33], v[52:53] op_sel_hi:[1,0]
	v_mul_f32_e32 v210, v210, v52
	v_xor_b32_e32 v50, 0x80000000, v206
	v_mov_b32_e32 v51, v50
	v_mov_b32_e32 v52, v50
	v_mov_b32_e32 v53, v50
	v_mov_b32_e32 v54, v50
	v_mov_b32_e32 v55, v50
	v_mov_b32_e32 v56, v50
	v_mov_b32_e32 v57, v50
	v_mov_b32_e32 v58, v50
	v_mov_b32_e32 v59, v50
	v_mov_b32_e32 v60, v50
	v_mov_b32_e32 v61, v50
	v_mov_b32_e32 v62, v50
	v_mov_b32_e32 v63, v50
	v_mov_b32_e32 v64, v50
	v_mov_b32_e32 v65, v50
	s_waitcnt lgkmcnt(0)
	s_barrier
	ds_read_b128 v[162:165], v193
	ds_read_b128 v[178:181], v193 offset:4608
	ds_read_b128 v[166:169], v193 offset:32
	ds_read_b128 v[182:185], v193 offset:4640
	ds_read_b128 v[170:173], v193 offset:64
	ds_read_b128 v[186:189], v193 offset:4672
	ds_read_b128 v[174:177], v193 offset:96
	ds_read_b128 v[82:85], v193 offset:4704
.Lattn_fx_top:
	s_add_i32 s11, s10, -1
	s_min_i32 s1, s11, s58
	s_mul_i32 s44, s1, 0xa0000
	s_add_u32 s44, s3, s44
	s_addc_u32 s45, s12, 0
	s_lshl_b32 s46, s1, 7
	s_add_u32 s46, s15, s46
	s_addc_u32 s47, s23, 0
	s_add_i32 s24, s10, -2
	s_cmp_lt_u32 s24, s16
	s_cselect_b64 s[0:1], -1, 0
	global_load_dwordx4 v[154:157], v252, s[44:45] offset:1024
	global_load_dwordx4 v[158:161], v253, s[46:47]
	v_exp_f32_e32 v66, v66
	v_exp_f32_e32 v67, v67
	v_exp_f32_e32 v68, v68
	v_exp_f32_e32 v69, v69
	v_add_f32_e32 v246, v66, v67
	v_cvt_pk_bf16_f32 v66, v66, v67
	s_waitcnt lgkmcnt(0)
	v_mfma_f32_32x32x16_bf16 v[114:129], v[162:165], v[130:133], v[50:65]
	ds_read_b128 v[86:89], v248 offset:36864
	ds_read_b128 v[216:219], v248 offset:41472
	v_exp_f32_e32 v70, v70
	v_exp_f32_e32 v71, v71
	v_add_f32_e32 v246, v68, v246
	v_add_f32_e32 v246, v69, v246
	v_cvt_pk_bf16_f32 v67, v68, v69
	v_mfma_f32_32x32x16_bf16 v[98:113], v[178:181], v[130:133], v[50:65]
	ds_read_b128 v[90:93], v248 offset:36896
	ds_read_b128 v[220:223], v248 offset:41504
	v_exp_f32_e32 v72, v72
	v_exp_f32_e32 v73, v73
	v_add_f32_e32 v246, v70, v246
	v_add_f32_e32 v246, v71, v246
	v_cvt_pk_bf16_f32 v68, v70, v71
	v_mfma_f32_32x32x16_bf16 v[114:129], v[166:169], v[134:137], v[114:129]
	ds_read_b128 v[94:97], v248 offset:36928
	ds_read_b128 v[224:227], v248 offset:41536
	v_exp_f32_e32 v74, v74
	v_exp_f32_e32 v75, v75
	v_add_f32_e32 v246, v72, v246
	v_add_f32_e32 v246, v73, v246
	v_cvt_pk_bf16_f32 v69, v72, v73
	v_mfma_f32_32x32x16_bf16 v[98:113], v[182:185], v[134:137], v[98:113]
	ds_read_b128 v[212:215], v248 offset:36960
	ds_read_b128 v[242:245], v248 offset:41568
	v_exp_f32_e32 v76, v76
	v_exp_f32_e32 v77, v77
	v_add_f32_e32 v246, v74, v246
	v_add_f32_e32 v246, v75, v246
	v_cvt_pk_bf16_f32 v70, v74, v75
	v_mfma_f32_32x32x16_bf16 v[114:129], v[170:173], v[138:141], v[114:129]
	s_cmp_ge_u32 s24, s16
	s_cbranch_scc1 .Lattn_fx_skipw1
	s_waitcnt vmcnt(2)
	ds_write_b128 v192, v[146:149] offset:18432
	ds_write_b128 v204, v[150:153] offset:27648
.Lattn_fx_skipw1:
	v_exp_f32_e32 v78, v78
	v_exp_f32_e32 v79, v79
	v_add_f32_e32 v246, v76, v246
	v_add_f32_e32 v246, v77, v246
	v_cvt_pk_bf16_f32 v71, v76, v77
	v_mfma_f32_32x32x16_bf16 v[98:113], v[186:189], v[138:141], v[98:113]
	v_exp_f32_e32 v80, v80
	v_exp_f32_e32 v81, v81
	v_add_f32_e32 v246, v78, v246
	v_add_f32_e32 v246, v79, v246
	v_cvt_pk_bf16_f32 v72, v78, v79
	v_mfma_f32_32x32x16_bf16 v[114:129], v[174:177], v[142:145], v[114:129]
	v_exp_f32_e32 v34, v34
	v_exp_f32_e32 v35, v35
	v_add_f32_e32 v246, v80, v246
	v_add_f32_e32 v246, v81, v246
	v_cvt_pk_bf16_f32 v73, v80, v81
	v_mfma_f32_32x32x16_bf16 v[98:113], v[82:85], v[142:145], v[98:113]
	v_exp_f32_e32 v36, v36
	v_exp_f32_e32 v37, v37
	v_add_f32_e32 v247, v34, v35
	v_cvt_pk_bf16_f32 v74, v34, v35
	s_waitcnt lgkmcnt(0)
	s_barrier
	ds_read_b128 v[162:165], v193 offset:18432
	ds_read_b128 v[178:181], v193 offset:23040
	ds_read_b128 v[166:169], v193 offset:18464
	ds_read_b128 v[182:185], v193 offset:23072
	ds_read_b128 v[170:173], v193 offset:18496
	ds_read_b128 v[186:189], v193 offset:23104
	ds_read_b128 v[174:177], v193 offset:18528
	ds_read_b128 v[82:85], v193 offset:23136
	v_mfma_f32_32x32x16_bf16 v[18:33], v[86:89], v[66:69], v[18:33]
	v_exp_f32_e32 v38, v38
	v_exp_f32_e32 v39, v39
	v_add_f32_e32 v247, v36, v247
	v_add_f32_e32 v247, v37, v247
	v_cvt_pk_bf16_f32 v75, v36, v37
	v_mfma_f32_32x32x16_bf16 v[2:17], v[216:219], v[66:69], v[2:17]
	v_exp_f32_e32 v40, v40
	v_exp_f32_e32 v41, v41
	v_add_f32_e32 v247, v38, v247
	v_add_f32_e32 v247, v39, v247
	v_cvt_pk_bf16_f32 v76, v38, v39
	v_mfma_f32_32x32x16_bf16 v[18:33], v[90:93], v[70:73], v[18:33]
	v_exp_f32_e32 v42, v42
	v_exp_f32_e32 v43, v43
	v_add_f32_e32 v247, v40, v247
	v_add_f32_e32 v247, v41, v247
	v_cvt_pk_bf16_f32 v77, v40, v41
	v_mfma_f32_32x32x16_bf16 v[2:17], v[220:223], v[70:73], v[2:17]
	v_exp_f32_e32 v44, v44
	v_exp_f32_e32 v45, v45
	v_add_f32_e32 v247, v42, v247
	v_add_f32_e32 v247, v43, v247
	v_cvt_pk_bf16_f32 v78, v42, v43
	v_mfma_f32_32x32x16_bf16 v[18:33], v[94:97], v[74:77], v[18:33]
	v_exp_f32_e32 v46, v46
	v_exp_f32_e32 v47, v47
	v_add_f32_e32 v247, v44, v247
	v_add_f32_e32 v247, v45, v247
	v_cvt_pk_bf16_f32 v79, v44, v45
	v_mfma_f32_32x32x16_bf16 v[2:17], v[224:227], v[74:77], v[2:17]
	v_exp_f32_e32 v48, v48
	v_exp_f32_e32 v49, v49
	v_add_f32_e32 v247, v46, v247
	v_add_f32_e32 v247, v47, v247
	v_cvt_pk_bf16_f32 v80, v46, v47
	v_cvt_pk_bf16_f32 v81, v48, v49
	v_add_f32_e32 v247, v48, v247
	v_add_f32_e32 v247, v49, v247
	v_mfma_f32_32x32x16_bf16 v[18:33], v[212:215], v[78:81], v[18:33]
	v_mfma_f32_32x32x16_bf16 v[2:17], v[242:245], v[78:81], v[2:17]
	v_add_f32_e32 v210, v210, v246
	v_add_f32_e32 v210, v210, v247
	s_min_i32 s24, s10, s58
	s_mul_i32 s44, s24, 0xa0000
	s_add_u32 s44, s3, s44
	s_addc_u32 s45, s12, 0
	s_lshl_b32 s46, s24, 7
	s_add_u32 s46, s15, s46
	s_addc_u32 s47, s23, 0
	global_load_dwordx4 v[146:149], v252, s[44:45] offset:1024
	global_load_dwordx4 v[150:153], v253, s[46:47]
	v_exp_f32_e32 v114, v114
	v_exp_f32_e32 v115, v115
	v_exp_f32_e32 v116, v116
	v_exp_f32_e32 v117, v117
	v_add_f32_e32 v246, v114, v115
	v_cvt_pk_bf16_f32 v114, v114, v115
	s_waitcnt lgkmcnt(0)
	v_mfma_f32_32x32x16_bf16 v[66:81], v[162:165], v[130:133], v[50:65]
	ds_read_b128 v[86:89], v248
	ds_read_b128 v[216:219], v248 offset:4608
	v_exp_f32_e32 v118, v118
	v_exp_f32_e32 v119, v119
	v_add_f32_e32 v246, v116, v246
	v_add_f32_e32 v246, v117, v246
	v_cvt_pk_bf16_f32 v115, v116, v117
	v_mfma_f32_32x32x16_bf16 v[34:49], v[178:181], v[130:133], v[50:65]
	ds_read_b128 v[90:93], v248 offset:32
	ds_read_b128 v[220:223], v248 offset:4640
	v_exp_f32_e32 v120, v120
	v_exp_f32_e32 v121, v121
	v_add_f32_e32 v246, v118, v246
	v_add_f32_e32 v246, v119, v246
	v_cvt_pk_bf16_f32 v116, v118, v119
	v_mfma_f32_32x32x16_bf16 v[66:81], v[166:169], v[134:137], v[66:81]
	ds_read_b128 v[94:97], v248 offset:64
	ds_read_b128 v[224:227], v248 offset:4672
	v_exp_f32_e32 v122, v122
	v_exp_f32_e32 v123, v123
	v_add_f32_e32 v246, v120, v246
	v_add_f32_e32 v246, v121, v246
	v_cvt_pk_bf16_f32 v117, v120, v121
	v_mfma_f32_32x32x16_bf16 v[34:49], v[182:185], v[134:137], v[34:49]
	ds_read_b128 v[212:215], v248 offset:96
	ds_read_b128 v[242:245], v248 offset:4704
	v_exp_f32_e32 v124, v124
	v_exp_f32_e32 v125, v125
	v_add_f32_e32 v246, v122, v246
	v_add_f32_e32 v246, v123, v246
	v_cvt_pk_bf16_f32 v118, v122, v123
	v_mfma_f32_32x32x16_bf16 v[66:81], v[170:173], v[138:141], v[66:81]
	s_cmp_ge_u32 s11, s16
	s_cbranch_scc1 .Lattn_fx_skipw2
	s_waitcnt vmcnt(2)
	ds_write_b128 v192, v[154:157] offset:55296
	ds_write_b128 v204, v[158:161] offset:64512
.Lattn_fx_skipw2:
	v_exp_f32_e32 v126, v126
	v_exp_f32_e32 v127, v127
	v_add_f32_e32 v246, v124, v246
	v_add_f32_e32 v246, v125, v246
	v_cvt_pk_bf16_f32 v119, v124, v125
	v_mfma_f32_32x32x16_bf16 v[34:49], v[186:189], v[138:141], v[34:49]
	v_exp_f32_e32 v128, v128
	v_exp_f32_e32 v129, v129
	v_add_f32_e32 v246, v126, v246
	v_add_f32_e32 v246, v127, v246
	v_cvt_pk_bf16_f32 v120, v126, v127
	v_mfma_f32_32x32x16_bf16 v[66:81], v[174:177], v[142:145], v[66:81]
	v_exp_f32_e32 v98, v98
	v_exp_f32_e32 v99, v99
	v_add_f32_e32 v246, v128, v246
	v_add_f32_e32 v246, v129, v246
	v_cvt_pk_bf16_f32 v121, v128, v129
	v_mfma_f32_32x32x16_bf16 v[34:49], v[82:85], v[142:145], v[34:49]
	v_exp_f32_e32 v100, v100
	v_exp_f32_e32 v101, v101
	v_add_f32_e32 v247, v98, v99
	v_cvt_pk_bf16_f32 v122, v98, v99
	s_waitcnt lgkmcnt(0)
	s_barrier
	ds_read_b128 v[162:165], v193 offset:55296
	ds_read_b128 v[178:181], v193 offset:59904
	ds_read_b128 v[166:169], v193 offset:55328
	ds_read_b128 v[182:185], v193 offset:59936
	ds_read_b128 v[170:173], v193 offset:55360
	ds_read_b128 v[186:189], v193 offset:59968
	ds_read_b128 v[174:177], v193 offset:55392
	ds_read_b128 v[82:85], v193 offset:60000
	v_mfma_f32_32x32x16_bf16 v[18:33], v[86:89], v[114:117], v[18:33]
	v_exp_f32_e32 v102, v102
	v_exp_f32_e32 v103, v103
	v_add_f32_e32 v247, v100, v247
	v_add_f32_e32 v247, v101, v247
	v_cvt_pk_bf16_f32 v123, v100, v101
	v_mfma_f32_32x32x16_bf16 v[2:17], v[216:219], v[114:117], v[2:17]
	v_exp_f32_e32 v104, v104
	v_exp_f32_e32 v105, v105
	v_add_f32_e32 v247, v102, v247
	v_add_f32_e32 v247, v103, v247
	v_cvt_pk_bf16_f32 v124, v102, v103
	v_mfma_f32_32x32x16_bf16 v[18:33], v[90:93], v[118:121], v[18:33]
	v_exp_f32_e32 v106, v106
	v_exp_f32_e32 v107, v107
	v_add_f32_e32 v247, v104, v247
	v_add_f32_e32 v247, v105, v247
	v_cvt_pk_bf16_f32 v125, v104, v105
	v_mfma_f32_32x32x16_bf16 v[2:17], v[220:223], v[118:121], v[2:17]
	v_exp_f32_e32 v108, v108
	v_exp_f32_e32 v109, v109
	v_add_f32_e32 v247, v106, v247
	v_add_f32_e32 v247, v107, v247
	v_cvt_pk_bf16_f32 v126, v106, v107
	v_mfma_f32_32x32x16_bf16 v[18:33], v[94:97], v[122:125], v[18:33]
	v_exp_f32_e32 v110, v110
	v_exp_f32_e32 v111, v111
	v_add_f32_e32 v247, v108, v247
	v_add_f32_e32 v247, v109, v247
	v_cvt_pk_bf16_f32 v127, v108, v109
	v_mfma_f32_32x32x16_bf16 v[2:17], v[224:227], v[122:125], v[2:17]
	v_exp_f32_e32 v112, v112
	v_exp_f32_e32 v113, v113
	v_add_f32_e32 v247, v110, v247
	v_add_f32_e32 v247, v111, v247
	v_cvt_pk_bf16_f32 v128, v110, v111
	v_cvt_pk_bf16_f32 v129, v112, v113
	v_add_f32_e32 v247, v112, v247
	v_add_f32_e32 v247, v113, v247
	v_mfma_f32_32x32x16_bf16 v[18:33], v[212:215], v[126:129], v[18:33]
	v_mfma_f32_32x32x16_bf16 v[2:17], v[242:245], v[126:129], v[2:17]
	v_add_f32_e32 v210, v210, v246
	v_add_f32_e32 v210, v210, v247
	s_add_i32 s10, s10, 2
	s_cmp_lt_u32 s11, s16
	s_cbranch_scc0 .Lattn_fx_exit0
	s_add_i32 s11, s10, -1
	s_min_i32 s1, s11, s58
	s_mul_i32 s44, s1, 0xa0000
	s_add_u32 s44, s3, s44
	s_addc_u32 s45, s12, 0
	s_lshl_b32 s46, s1, 7
	s_add_u32 s46, s15, s46
	s_addc_u32 s47, s23, 0
	s_add_i32 s24, s10, -2
	s_cmp_lt_u32 s24, s16
	s_cselect_b64 s[0:1], -1, 0
	global_load_dwordx4 v[154:157], v252, s[44:45] offset:1024
	global_load_dwordx4 v[158:161], v253, s[46:47]
	v_exp_f32_e32 v66, v66
	v_exp_f32_e32 v67, v67
	v_exp_f32_e32 v68, v68
	v_exp_f32_e32 v69, v69
	v_add_f32_e32 v246, v66, v67
	v_cvt_pk_bf16_f32 v66, v66, v67
	s_waitcnt lgkmcnt(0)
	v_mfma_f32_32x32x16_bf16 v[114:129], v[162:165], v[130:133], v[50:65]
	ds_read_b128 v[86:89], v248 offset:18432
	ds_read_b128 v[216:219], v248 offset:23040
	v_exp_f32_e32 v70, v70
	v_exp_f32_e32 v71, v71
	v_add_f32_e32 v246, v68, v246
	v_add_f32_e32 v246, v69, v246
	v_cvt_pk_bf16_f32 v67, v68, v69
	v_mfma_f32_32x32x16_bf16 v[98:113], v[178:181], v[130:133], v[50:65]
	ds_read_b128 v[90:93], v248 offset:18464
	ds_read_b128 v[220:223], v248 offset:23072
	v_exp_f32_e32 v72, v72
	v_exp_f32_e32 v73, v73
	v_add_f32_e32 v246, v70, v246
	v_add_f32_e32 v246, v71, v246
	v_cvt_pk_bf16_f32 v68, v70, v71
	v_mfma_f32_32x32x16_bf16 v[114:129], v[166:169], v[134:137], v[114:129]
	ds_read_b128 v[94:97], v248 offset:18496
	ds_read_b128 v[224:227], v248 offset:23104
	v_exp_f32_e32 v74, v74
	v_exp_f32_e32 v75, v75
	v_add_f32_e32 v246, v72, v246
	v_add_f32_e32 v246, v73, v246
	v_cvt_pk_bf16_f32 v69, v72, v73
	v_mfma_f32_32x32x16_bf16 v[98:113], v[182:185], v[134:137], v[98:113]
	ds_read_b128 v[212:215], v248 offset:18528
	ds_read_b128 v[242:245], v248 offset:23136
	v_exp_f32_e32 v76, v76
	v_exp_f32_e32 v77, v77
	v_add_f32_e32 v246, v74, v246
	v_add_f32_e32 v246, v75, v246
	v_cvt_pk_bf16_f32 v70, v74, v75
	v_mfma_f32_32x32x16_bf16 v[114:129], v[170:173], v[138:141], v[114:129]
	s_cmp_ge_u32 s24, s16
	s_cbranch_scc1 .Lattn_fx_skipw3
	s_waitcnt vmcnt(2)
	ds_write_b128 v192, v[146:149] offset:36864
	ds_write_b128 v204, v[150:153] offset:46080
.Lattn_fx_skipw3:
	v_exp_f32_e32 v78, v78
	v_exp_f32_e32 v79, v79
	v_add_f32_e32 v246, v76, v246
	v_add_f32_e32 v246, v77, v246
	v_cvt_pk_bf16_f32 v71, v76, v77
	v_mfma_f32_32x32x16_bf16 v[98:113], v[186:189], v[138:141], v[98:113]
	v_exp_f32_e32 v80, v80
	v_exp_f32_e32 v81, v81
	v_add_f32_e32 v246, v78, v246
	v_add_f32_e32 v246, v79, v246
	v_cvt_pk_bf16_f32 v72, v78, v79
	v_mfma_f32_32x32x16_bf16 v[114:129], v[174:177], v[142:145], v[114:129]
	v_exp_f32_e32 v34, v34
	v_exp_f32_e32 v35, v35
	v_add_f32_e32 v246, v80, v246
	v_add_f32_e32 v246, v81, v246
	v_cvt_pk_bf16_f32 v73, v80, v81
	v_mfma_f32_32x32x16_bf16 v[98:113], v[82:85], v[142:145], v[98:113]
	v_exp_f32_e32 v36, v36
	v_exp_f32_e32 v37, v37
	v_add_f32_e32 v247, v34, v35
	v_cvt_pk_bf16_f32 v74, v34, v35
	s_waitcnt lgkmcnt(0)
	s_barrier
	ds_read_b128 v[162:165], v193 offset:36864
	ds_read_b128 v[178:181], v193 offset:41472
	ds_read_b128 v[166:169], v193 offset:36896
	ds_read_b128 v[182:185], v193 offset:41504
	ds_read_b128 v[170:173], v193 offset:36928
	ds_read_b128 v[186:189], v193 offset:41536
	ds_read_b128 v[174:177], v193 offset:36960
	ds_read_b128 v[82:85], v193 offset:41568
	v_mfma_f32_32x32x16_bf16 v[18:33], v[86:89], v[66:69], v[18:33]
	v_exp_f32_e32 v38, v38
	v_exp_f32_e32 v39, v39
	v_add_f32_e32 v247, v36, v247
	v_add_f32_e32 v247, v37, v247
	v_cvt_pk_bf16_f32 v75, v36, v37
	v_mfma_f32_32x32x16_bf16 v[2:17], v[216:219], v[66:69], v[2:17]
	v_exp_f32_e32 v40, v40
	v_exp_f32_e32 v41, v41
	v_add_f32_e32 v247, v38, v247
	v_add_f32_e32 v247, v39, v247
	v_cvt_pk_bf16_f32 v76, v38, v39
	v_mfma_f32_32x32x16_bf16 v[18:33], v[90:93], v[70:73], v[18:33]
	v_exp_f32_e32 v42, v42
	v_exp_f32_e32 v43, v43
	v_add_f32_e32 v247, v40, v247
	v_add_f32_e32 v247, v41, v247
	v_cvt_pk_bf16_f32 v77, v40, v41
	v_mfma_f32_32x32x16_bf16 v[2:17], v[220:223], v[70:73], v[2:17]
	v_exp_f32_e32 v44, v44
	v_exp_f32_e32 v45, v45
	v_add_f32_e32 v247, v42, v247
	v_add_f32_e32 v247, v43, v247
	v_cvt_pk_bf16_f32 v78, v42, v43
	v_mfma_f32_32x32x16_bf16 v[18:33], v[94:97], v[74:77], v[18:33]
	v_exp_f32_e32 v46, v46
	v_exp_f32_e32 v47, v47
	v_add_f32_e32 v247, v44, v247
	v_add_f32_e32 v247, v45, v247
	v_cvt_pk_bf16_f32 v79, v44, v45
	v_mfma_f32_32x32x16_bf16 v[2:17], v[224:227], v[74:77], v[2:17]
	v_exp_f32_e32 v48, v48
	v_exp_f32_e32 v49, v49
	v_add_f32_e32 v247, v46, v247
	v_add_f32_e32 v247, v47, v247
	v_cvt_pk_bf16_f32 v80, v46, v47
	v_cvt_pk_bf16_f32 v81, v48, v49
	v_add_f32_e32 v247, v48, v247
	v_add_f32_e32 v247, v49, v247
	v_mfma_f32_32x32x16_bf16 v[18:33], v[212:215], v[78:81], v[18:33]
	v_mfma_f32_32x32x16_bf16 v[2:17], v[242:245], v[78:81], v[2:17]
	v_add_f32_e32 v210, v210, v246
	v_add_f32_e32 v210, v210, v247
	s_min_i32 s24, s10, s58
	s_mul_i32 s44, s24, 0xa0000
	s_add_u32 s44, s3, s44
	s_addc_u32 s45, s12, 0
	s_lshl_b32 s46, s24, 7
	s_add_u32 s46, s15, s46
	s_addc_u32 s47, s23, 0
	global_load_dwordx4 v[146:149], v252, s[44:45] offset:1024
	global_load_dwordx4 v[150:153], v253, s[46:47]
	v_exp_f32_e32 v114, v114
	v_exp_f32_e32 v115, v115
	v_exp_f32_e32 v116, v116
	v_exp_f32_e32 v117, v117
	v_add_f32_e32 v246, v114, v115
	v_cvt_pk_bf16_f32 v114, v114, v115
	s_waitcnt lgkmcnt(0)
	v_mfma_f32_32x32x16_bf16 v[66:81], v[162:165], v[130:133], v[50:65]
	ds_read_b128 v[86:89], v248 offset:55296
	ds_read_b128 v[216:219], v248 offset:59904
	v_exp_f32_e32 v118, v118
	v_exp_f32_e32 v119, v119
	v_add_f32_e32 v246, v116, v246
	v_add_f32_e32 v246, v117, v246
	v_cvt_pk_bf16_f32 v115, v116, v117
	v_mfma_f32_32x32x16_bf16 v[34:49], v[178:181], v[130:133], v[50:65]
	ds_read_b128 v[90:93], v248 offset:55328
	ds_read_b128 v[220:223], v248 offset:59936
	v_exp_f32_e32 v120, v120
	v_exp_f32_e32 v121, v121
	v_add_f32_e32 v246, v118, v246
	v_add_f32_e32 v246, v119, v246
	v_cvt_pk_bf16_f32 v116, v118, v119
	v_mfma_f32_32x32x16_bf16 v[66:81], v[166:169], v[134:137], v[66:81]
	ds_read_b128 v[94:97], v248 offset:55360
	ds_read_b128 v[224:227], v248 offset:59968
	v_exp_f32_e32 v122, v122
	v_exp_f32_e32 v123, v123
	v_add_f32_e32 v246, v120, v246
	v_add_f32_e32 v246, v121, v246
	v_cvt_pk_bf16_f32 v117, v120, v121
	v_mfma_f32_32x32x16_bf16 v[34:49], v[182:185], v[134:137], v[34:49]
	ds_read_b128 v[212:215], v248 offset:55392
	ds_read_b128 v[242:245], v248 offset:60000
	v_exp_f32_e32 v124, v124
	v_exp_f32_e32 v125, v125
	v_add_f32_e32 v246, v122, v246
	v_add_f32_e32 v246, v123, v246
	v_cvt_pk_bf16_f32 v118, v122, v123
	v_mfma_f32_32x32x16_bf16 v[66:81], v[170:173], v[138:141], v[66:81]
	s_cmp_ge_u32 s11, s16
	s_cbranch_scc1 .Lattn_fx_skipw4
	s_waitcnt vmcnt(2)
	ds_write_b128 v192, v[154:157]
	ds_write_b128 v204, v[158:161] offset:9216
; template <int HD, int MODE> ...
;     ...
;     int t = t0;
;     for (; t + 1 < t1; t += 2) { ATT_STEP(sa0, sa1, sb0, sb1, t, kstB, vstB, kstA, vstA); ATT_STEP(sb0, sb1, sa0, sa1, t + 1, kstA, vstA, kstB, vstB); }
;     if (t < t1) ATT_STEP(sa0, sa1, sb0, sb1, t, kstB, vstB, kstA, vstA);
.Lattn_fx_skipw4:
	v_exp_f32_e32 v126, v126
	v_exp_f32_e32 v127, v127
	v_add_f32_e32 v246, v124, v246
	v_add_f32_e32 v246, v125, v246
	v_cvt_pk_bf16_f32 v119, v124, v125
	v_mfma_f32_32x32x16_bf16 v[34:49], v[186:189], v[138:141], v[34:49]
	v_exp_f32_e32 v128, v128
	v_exp_f32_e32 v129, v129
	v_add_f32_e32 v246, v126, v246
	v_add_f32_e32 v246, v127, v246
	v_cvt_pk_bf16_f32 v120, v126, v127
	v_mfma_f32_32x32x16_bf16 v[66:81], v[174:177], v[142:145], v[66:81]
	v_exp_f32_e32 v98, v98
	v_exp_f32_e32 v99, v99
	v_add_f32_e32 v246, v128, v246
	v_add_f32_e32 v246, v129, v246
	v_cvt_pk_bf16_f32 v121, v128, v129
	v_mfma_f32_32x32x16_bf16 v[34:49], v[82:85], v[142:145], v[34:49]
	v_exp_f32_e32 v100, v100
	v_exp_f32_e32 v101, v101
	v_add_f32_e32 v247, v98, v99
	v_cvt_pk_bf16_f32 v122, v98, v99
	s_waitcnt lgkmcnt(0)
	s_barrier
	ds_read_b128 v[162:165], v193
	ds_read_b128 v[178:181], v193 offset:4608
	ds_read_b128 v[166:169], v193 offset:32
	ds_read_b128 v[182:185], v193 offset:4640
	ds_read_b128 v[170:173], v193 offset:64
	ds_read_b128 v[186:189], v193 offset:4672
	ds_read_b128 v[174:177], v193 offset:96
	ds_read_b128 v[82:85], v193 offset:4704
	v_mfma_f32_32x32x16_bf16 v[18:33], v[86:89], v[114:117], v[18:33]
	v_exp_f32_e32 v102, v102
	v_exp_f32_e32 v103, v103
	v_add_f32_e32 v247, v100, v247
	v_add_f32_e32 v247, v101, v247
	v_cvt_pk_bf16_f32 v123, v100, v101
	v_mfma_f32_32x32x16_bf16 v[2:17], v[216:219], v[114:117], v[2:17]
	v_exp_f32_e32 v104, v104
	v_exp_f32_e32 v105, v105
	v_add_f32_e32 v247, v102, v247
	v_add_f32_e32 v247, v103, v247
	v_cvt_pk_bf16_f32 v124, v102, v103
	v_mfma_f32_32x32x16_bf16 v[18:33], v[90:93], v[118:121], v[18:33]
	v_exp_f32_e32 v106, v106
	v_exp_f32_e32 v107, v107
	v_add_f32_e32 v247, v104, v247
	v_add_f32_e32 v247, v105, v247
	v_cvt_pk_bf16_f32 v125, v104, v105
	v_mfma_f32_32x32x16_bf16 v[2:17], v[220:223], v[118:121], v[2:17]
	v_exp_f32_e32 v108, v108
	v_exp_f32_e32 v109, v109
	v_add_f32_e32 v247, v106, v247
	v_add_f32_e32 v247, v107, v247
	v_cvt_pk_bf16_f32 v126, v106, v107
	v_mfma_f32_32x32x16_bf16 v[18:33], v[94:97], v[122:125], v[18:33]
	v_exp_f32_e32 v110, v110
	v_exp_f32_e32 v111, v111
	v_add_f32_e32 v247, v108, v247
	v_add_f32_e32 v247, v109, v247
	v_cvt_pk_bf16_f32 v127, v108, v109
	v_mfma_f32_32x32x16_bf16 v[2:17], v[224:227], v[122:125], v[2:17]
	v_exp_f32_e32 v112, v112
	v_exp_f32_e32 v113, v113
	v_add_f32_e32 v247, v110, v247
	v_add_f32_e32 v247, v111, v247
	v_cvt_pk_bf16_f32 v128, v110, v111
	v_cvt_pk_bf16_f32 v129, v112, v113
	v_add_f32_e32 v247, v112, v247
	v_add_f32_e32 v247, v113, v247
	v_mfma_f32_32x32x16_bf16 v[18:33], v[212:215], v[126:129], v[18:33]
	v_mfma_f32_32x32x16_bf16 v[2:17], v[242:245], v[126:129], v[2:17]
	v_add_f32_e32 v210, v210, v246
	v_add_f32_e32 v210, v210, v247
	s_add_i32 s10, s10, 2
	s_cmp_lt_u32 s11, s16
	s_cbranch_scc0 .Lattn_fx_exit1
	s_branch .Lattn_fx_top
.Lattn_fx_exit0:
	s_waitcnt lgkmcnt(0)
	s_movk_i32 s2, 0x4800
	s_branch .LBB0_508
.Lattn_fx_exit1:
	s_waitcnt lgkmcnt(0)
	s_mov_b32 s2, 0x9000
	s_branch .LBB0_508
